# attention chunk: QK reads up front, V frags prefetched, softmax+PV hand-scheduled (max3 tree, permlane swap, packed sub/sum); G4 fix loop batched
# speedup vs baseline: 1.0304x; 1.0159x over previous
.LBB0_474:
	v_pk_add_f32 v[50:51], v[50:51], v[190:191] op_sel_hi:[1,0] neg_lo:[0,1] neg_hi:[0,1]
	v_pk_add_f32 v[52:53], v[52:53], v[190:191] op_sel_hi:[1,0] neg_lo:[0,1] neg_hi:[0,1]
	v_pk_add_f32 v[54:55], v[54:55], v[190:191] op_sel_hi:[1,0] neg_lo:[0,1] neg_hi:[0,1]
	v_pk_add_f32 v[56:57], v[56:57], v[190:191] op_sel_hi:[1,0] neg_lo:[0,1] neg_hi:[0,1]
	v_exp_f32_e32 v50, v50
	v_exp_f32_e32 v51, v51
	v_exp_f32_e32 v52, v52
	v_exp_f32_e32 v53, v53
	v_exp_f32_e32 v54, v54
	v_exp_f32_e32 v55, v55
	v_exp_f32_e32 v56, v56
	v_exp_f32_e32 v57, v57
	v_cvt_pk_bf16_f32 v226, v50, v51
	v_cvt_pk_bf16_f32 v227, v52, v53
	v_cvt_pk_bf16_f32 v228, v54, v55
	v_pk_add_f32 v[58:59], v[58:59], v[190:191] op_sel_hi:[1,0] neg_lo:[0,1] neg_hi:[0,1]
	v_cvt_pk_bf16_f32 v229, v56, v57
	v_pk_add_f32 v[60:61], v[60:61], v[190:191] op_sel_hi:[1,0] neg_lo:[0,1] neg_hi:[0,1]
	v_pk_add_f32 v[62:63], v[62:63], v[190:191] op_sel_hi:[1,0] neg_lo:[0,1] neg_hi:[0,1]
	v_mfma_f32_32x32x16_bf16 v[2:17], v[192:195], v[226:229], v[2:17]
	v_mfma_f32_32x32x16_bf16 v[18:33], v[208:211], v[226:229], v[18:33]
	v_pk_add_f32 v[64:65], v[64:65], v[190:191] op_sel_hi:[1,0] neg_lo:[0,1] neg_hi:[0,1]
	v_exp_f32_e32 v58, v58
	v_exp_f32_e32 v59, v59
	v_exp_f32_e32 v60, v60
	v_exp_f32_e32 v61, v61
	v_exp_f32_e32 v62, v62
	v_exp_f32_e32 v63, v63
	v_exp_f32_e32 v64, v64
	v_exp_f32_e32 v65, v65
	v_pk_add_f32 v[66:67], v[50:51], v[52:53]
	v_pk_add_f32 v[66:67], v[66:67], v[54:55]
	v_pk_add_f32 v[66:67], v[66:67], v[56:57]
	v_cvt_pk_bf16_f32 v230, v58, v59
	v_cvt_pk_bf16_f32 v231, v60, v61
	v_cvt_pk_bf16_f32 v232, v62, v63
	v_pk_add_f32 v[34:35], v[34:35], v[190:191] op_sel_hi:[1,0] neg_lo:[0,1] neg_hi:[0,1]
	v_cvt_pk_bf16_f32 v233, v64, v65
	v_pk_add_f32 v[36:37], v[36:37], v[190:191] op_sel_hi:[1,0] neg_lo:[0,1] neg_hi:[0,1]
	v_pk_add_f32 v[38:39], v[38:39], v[190:191] op_sel_hi:[1,0] neg_lo:[0,1] neg_hi:[0,1]
	v_mfma_f32_32x32x16_bf16 v[2:17], v[196:199], v[230:233], v[2:17]
	v_mfma_f32_32x32x16_bf16 v[18:33], v[214:217], v[230:233], v[18:33]
	v_pk_add_f32 v[40:41], v[40:41], v[190:191] op_sel_hi:[1,0] neg_lo:[0,1] neg_hi:[0,1]
	v_exp_f32_e32 v34, v34
	v_exp_f32_e32 v35, v35
	v_exp_f32_e32 v36, v36
	v_exp_f32_e32 v37, v37
	v_exp_f32_e32 v38, v38
	v_exp_f32_e32 v39, v39
	v_exp_f32_e32 v40, v40
	v_exp_f32_e32 v41, v41
	v_pk_add_f32 v[66:67], v[66:67], v[58:59]
	v_pk_add_f32 v[66:67], v[66:67], v[60:61]
	v_pk_add_f32 v[66:67], v[66:67], v[62:63]
	v_pk_add_f32 v[66:67], v[66:67], v[64:65]
	v_cvt_pk_bf16_f32 v234, v34, v35
	v_cvt_pk_bf16_f32 v235, v36, v37
	v_cvt_pk_bf16_f32 v236, v38, v39
	v_pk_add_f32 v[42:43], v[42:43], v[190:191] op_sel_hi:[1,0] neg_lo:[0,1] neg_hi:[0,1]
	v_cvt_pk_bf16_f32 v237, v40, v41
	v_pk_add_f32 v[44:45], v[44:45], v[190:191] op_sel_hi:[1,0] neg_lo:[0,1] neg_hi:[0,1]
	v_pk_add_f32 v[46:47], v[46:47], v[190:191] op_sel_hi:[1,0] neg_lo:[0,1] neg_hi:[0,1]
	v_mfma_f32_32x32x16_bf16 v[2:17], v[200:203], v[234:237], v[2:17]
	v_mfma_f32_32x32x16_bf16 v[18:33], v[218:221], v[234:237], v[18:33]
	v_pk_add_f32 v[48:49], v[48:49], v[190:191] op_sel_hi:[1,0] neg_lo:[0,1] neg_hi:[0,1]
	v_exp_f32_e32 v42, v42
	v_exp_f32_e32 v43, v43
	v_exp_f32_e32 v44, v44
	v_exp_f32_e32 v45, v45
	v_exp_f32_e32 v46, v46
	v_exp_f32_e32 v47, v47
	v_exp_f32_e32 v48, v48
	v_exp_f32_e32 v49, v49
	v_pk_add_f32 v[68:69], v[34:35], v[36:37]
	v_pk_add_f32 v[68:69], v[68:69], v[38:39]
	v_pk_add_f32 v[68:69], v[68:69], v[40:41]
	v_cvt_pk_bf16_f32 v238, v42, v43
	v_cvt_pk_bf16_f32 v239, v44, v45
	v_cvt_pk_bf16_f32 v240, v46, v47
	v_cvt_pk_bf16_f32 v241, v48, v49
	v_pk_add_f32 v[68:69], v[68:69], v[42:43]
	v_pk_add_f32 v[68:69], v[68:69], v[44:45]
	v_mfma_f32_32x32x16_bf16 v[2:17], v[204:207], v[238:241], v[2:17]
	v_mfma_f32_32x32x16_bf16 v[18:33], v[222:225], v[238:241], v[18:33]
	v_pk_add_f32 v[68:69], v[68:69], v[46:47]
	v_pk_add_f32 v[68:69], v[68:69], v[48:49]
	v_pk_add_f32 v[66:67], v[66:67], v[68:69]
	v_add_f32_e32 v66, v66, v67
	v_add_f32_e32 v149, v149, v66

.LBB0_478:
	s_or_saveexec_b64 s[72:73], s[72:73]
	v_mov_b64_e32 v[40:41], s[90:91]
	s_xor_b64 exec, exec, s[72:73]
	v_ashrrev_i32_e32 v39, 31, v38
	v_lshlrev_b64 v[34:35], 7, v[38:39]
	v_lshl_add_u64 v[34:35], v[156:157], 0, v[34:35]
	v_ashrrev_i32_e32 v37, 31, v36
	v_mov_b64_e32 v[40:41], v[158:159]
	s_or_b64 exec, exec, s[72:73]
	v_mov_b32_e32 v141, v133
	v_lshlrev_b64 v[36:37], 13, v[36:37]
	v_lshl_add_u64 v[38:39], v[34:35], 0, v[132:133]
	v_mov_b32_e32 v137, v133
	v_lshl_add_u64 v[34:35], v[34:35], 0, v[140:141]
	v_lshl_add_u64 v[36:37], v[40:41], 0, v[36:37]
	v_lshl_add_u64 v[38:39], v[38:39], 0, v[136:137]
	v_lshl_add_u64 v[34:35], v[34:35], 0, v[136:137]
	global_load_dwordx4 v[126:129], v[38:39], off
	global_load_dwordx4 v[122:125], v[34:35], off
	v_lshl_add_u64 v[34:35], v[36:37], 0, v[132:133]
	v_lshl_add_u64 v[34:35], v[34:35], 0, v[136:137]
	v_lshl_add_u64 v[36:37], v[36:37], 0, v[140:141]
	v_lshl_add_u64 v[36:37], v[36:37], 0, v[136:137]
	global_load_dwordx4 v[118:121], v[34:35], off
	global_load_dwordx4 v[114:117], v[36:37], off
	s_cmp_gt_u32 s3, 7
	s_cselect_b64 s[72:73], -1, 0
	s_and_b64 s[94:95], s[0:1], s[72:73]
	v_mov_b32_e32 v66, 0
	s_mov_b64 vcc, -1
	s_and_saveexec_b64 s[76:77], s[94:95]
	v_add_u32_e32 v34, s3, v189
	v_cmp_ge_i32_e32 vcc, v34, v182
	v_cmp_lt_i32_e64 s[72:73], v34, v186
	s_and_b64 s[72:73], vcc, s[72:73]
	s_orn2_b64 vcc, s[72:73], exec
	v_mov_b32_e32 v66, v188
	s_or_b64 exec, exec, s[76:77]
	s_and_saveexec_b64 s[72:73], vcc
	s_cbranch_execz .LBB0_475
	s_bitcmp1_b32 s3, 0
	s_cselect_b32 s3, 0x4800, 0
	v_add_u32_e32 v137, s3, v173
	ds_read_b128 v[192:195], v137
	ds_read_b128 v[208:211], v137 offset:4608
	ds_read_b128 v[196:199], v137 offset:32
	ds_read_b128 v[214:217], v137 offset:4640
	ds_read_b128 v[200:203], v137 offset:64
	ds_read_b128 v[218:221], v137 offset:4672
	ds_read_b128 v[204:207], v137 offset:96
	ds_read_b128 v[222:225], v137 offset:4704
	s_waitcnt lgkmcnt(6)
	v_mfma_f32_32x32x16_bf16 v[50:65], v[192:195], v[98:101], 0
	v_mfma_f32_32x32x16_bf16 v[34:49], v[208:211], v[98:101], 0
	s_waitcnt lgkmcnt(4)
	v_mfma_f32_32x32x16_bf16 v[50:65], v[196:199], v[102:105], v[50:65]
	v_mfma_f32_32x32x16_bf16 v[34:49], v[214:217], v[102:105], v[34:49]
	s_waitcnt lgkmcnt(2)
	v_mfma_f32_32x32x16_bf16 v[50:65], v[200:203], v[106:109], v[50:65]
	v_mfma_f32_32x32x16_bf16 v[34:49], v[218:221], v[106:109], v[34:49]
	s_waitcnt lgkmcnt(0)
	v_mfma_f32_32x32x16_bf16 v[50:65], v[204:207], v[110:113], v[50:65]
	v_mfma_f32_32x32x16_bf16 v[34:49], v[222:225], v[110:113], v[34:49]
	ds_read_b128 v[192:195], v137 offset:9216
	ds_read_b128 v[208:211], v137 offset:13824
	ds_read_b128 v[196:199], v137 offset:9248
	ds_read_b128 v[214:217], v137 offset:13856
	ds_read_b128 v[200:203], v137 offset:9280
	ds_read_b128 v[218:221], v137 offset:13888
	ds_read_b128 v[204:207], v137 offset:9312
	ds_read_b128 v[222:225], v137 offset:13920
	s_and_saveexec_b64 vcc, s[94:95]
	s_cbranch_execz .LBB0_549
	v_lshl_add_u32 v141, v66, 2, v187
	v_add_u32_e32 v141, 0x903c, v141
	v_mov_b32_e32 v246, 0xff800000
	ds_read2_b32 v[82:83], v141 offset0:0 offset1:1
	ds_read2_b32 v[84:85], v141 offset0:2 offset1:3
	ds_read2_b32 v[86:87], v141 offset0:8 offset1:9
	ds_read2_b32 v[88:89], v141 offset0:10 offset1:11
	ds_read2_b32 v[90:91], v141 offset0:16 offset1:17
	ds_read2_b32 v[92:93], v141 offset0:18 offset1:19
	ds_read2_b32 v[94:95], v141 offset0:24 offset1:25
	ds_read2_b32 v[96:97], v141 offset0:26 offset1:27
	ds_read2_b32 v[66:67], v141 offset0:32 offset1:33
	ds_read2_b32 v[68:69], v141 offset0:34 offset1:35
	ds_read2_b32 v[70:71], v141 offset0:40 offset1:41
	ds_read2_b32 v[72:73], v141 offset0:42 offset1:43
	ds_read2_b32 v[74:75], v141 offset0:48 offset1:49
	ds_read2_b32 v[76:77], v141 offset0:50 offset1:51
	ds_read2_b32 v[78:79], v141 offset0:56 offset1:57
	ds_read2_b32 v[80:81], v141 offset0:58 offset1:59
	s_waitcnt lgkmcnt(8)
	v_pk_add_f32 v[82:83], v[50:51], v[82:83]
	v_pk_add_f32 v[84:85], v[52:53], v[84:85]
	v_pk_add_f32 v[86:87], v[54:55], v[86:87]
	v_pk_add_f32 v[88:89], v[56:57], v[88:89]
	v_pk_add_f32 v[90:91], v[58:59], v[90:91]
	v_pk_add_f32 v[92:93], v[60:61], v[92:93]
	v_pk_add_f32 v[94:95], v[62:63], v[94:95]
	v_pk_add_f32 v[96:97], v[64:65], v[96:97]
	v_cndmask_b32_e64 v50, v246, v82, s[4:5]
	v_cndmask_b32_e64 v51, v246, v83, s[8:9]
	v_cndmask_b32_e64 v52, v246, v84, s[12:13]
	v_cndmask_b32_e64 v53, v246, v85, s[16:17]
	v_cndmask_b32_e64 v54, v246, v86, s[20:21]
	v_cndmask_b32_e64 v55, v246, v87, s[24:25]
	v_cndmask_b32_e64 v56, v246, v88, s[28:29]
	v_cndmask_b32_e64 v57, v246, v89, s[34:35]
	v_cndmask_b32_e64 v58, v246, v90, s[38:39]
	v_cndmask_b32_e64 v59, v246, v91, s[42:43]
	v_cndmask_b32_e64 v60, v246, v92, s[46:47]
	v_cndmask_b32_e64 v61, v246, v93, s[50:51]
	v_cndmask_b32_e64 v62, v246, v94, s[54:55]
	v_cndmask_b32_e64 v63, v246, v95, s[58:59]
	v_cndmask_b32_e64 v64, v246, v96, s[62:63]
	v_cndmask_b32_e64 v65, v246, v97, s[66:67]
	s_waitcnt lgkmcnt(0)
	v_pk_add_f32 v[66:67], v[34:35], v[66:67]
	v_pk_add_f32 v[68:69], v[36:37], v[68:69]
	v_pk_add_f32 v[70:71], v[38:39], v[70:71]
	v_pk_add_f32 v[72:73], v[40:41], v[72:73]
	v_pk_add_f32 v[74:75], v[42:43], v[74:75]
	v_pk_add_f32 v[76:77], v[44:45], v[76:77]
	v_pk_add_f32 v[78:79], v[46:47], v[78:79]
	v_pk_add_f32 v[80:81], v[48:49], v[80:81]
	v_cndmask_b32_e64 v34, v246, v66, s[6:7]
	v_cndmask_b32_e64 v35, v246, v67, s[10:11]
	v_cndmask_b32_e64 v36, v246, v68, s[14:15]
	v_cndmask_b32_e64 v37, v246, v69, s[18:19]
	v_cndmask_b32_e64 v38, v246, v70, s[22:23]
	v_cndmask_b32_e64 v39, v246, v71, s[26:27]
	v_cndmask_b32_e64 v40, v246, v72, s[30:31]
	v_cndmask_b32_e64 v41, v246, v73, s[36:37]
	v_cndmask_b32_e64 v42, v246, v74, s[40:41]
	v_cndmask_b32_e64 v43, v246, v75, s[44:45]
	v_cndmask_b32_e64 v44, v246, v76, s[48:49]
	v_cndmask_b32_e64 v45, v246, v77, s[52:53]
	v_cndmask_b32_e64 v46, v246, v78, s[56:57]
	v_cndmask_b32_e64 v47, v246, v79, s[60:61]
	v_cndmask_b32_e64 v48, v246, v80, s[64:65]
	v_cndmask_b32_e64 v49, v246, v81, s[68:69]
.LBB0_549:
	s_or_b64 exec, exec, vcc
	s_nop 1
	v_max3_f32 v66, v50, v51, v52
	v_max3_f32 v67, v53, v54, v55
	v_max3_f32 v68, v56, v57, v58
	v_max3_f32 v69, v59, v60, v61
	v_max3_f32 v66, v66, v62, v63
	v_max3_f32 v67, v67, v64, v65
	v_max3_f32 v68, v68, v34, v35
	v_max3_f32 v69, v69, v36, v37
	v_max3_f32 v66, v66, v38, v39
	v_max3_f32 v67, v67, v40, v41
	v_max3_f32 v68, v68, v42, v43
	v_max3_f32 v69, v69, v44, v45
	v_max3_f32 v66, v66, v46, v47
	v_max3_f32 v67, v67, v48, v49
	v_max3_f32 v66, v66, v67, v68
	v_max_f32_e32 v66, v66, v69
	v_mov_b32_e32 v67, v66
	s_nop 1
	v_permlane32_swap_b32_e32 v66, v67
	v_add_f32_e32 v68, 0x41000000, v190
	v_max_f32_e32 v66, v66, v67
	v_cmp_gt_f32_e32 vcc, v66, v68
	s_cbranch_vccz .LBB0_474
	v_max_f32_e32 v66, v66, v66
	v_max_f32_e32 v67, v190, v190
	v_max_f32_e32 v67, v67, v66
	v_sub_f32_e32 v66, v190, v67
	v_exp_f32_e32 v66, v66
	v_mov_b32_e32 v190, v67
	v_pk_mul_f32 v[16:17], v[16:17], v[66:67] op_sel_hi:[1,0]
	v_pk_mul_f32 v[14:15], v[14:15], v[66:67] op_sel_hi:[1,0]
	v_pk_mul_f32 v[12:13], v[12:13], v[66:67] op_sel_hi:[1,0]
	v_pk_mul_f32 v[10:11], v[10:11], v[66:67] op_sel_hi:[1,0]
	v_pk_mul_f32 v[8:9], v[8:9], v[66:67] op_sel_hi:[1,0]
	v_pk_mul_f32 v[6:7], v[6:7], v[66:67] op_sel_hi:[1,0]
	v_pk_mul_f32 v[4:5], v[4:5], v[66:67] op_sel_hi:[1,0]
	v_pk_mul_f32 v[2:3], v[2:3], v[66:67] op_sel_hi:[1,0]
	v_pk_mul_f32 v[32:33], v[32:33], v[66:67] op_sel_hi:[1,0]
	v_pk_mul_f32 v[30:31], v[30:31], v[66:67] op_sel_hi:[1,0]
	v_pk_mul_f32 v[28:29], v[28:29], v[66:67] op_sel_hi:[1,0]
	v_pk_mul_f32 v[26:27], v[26:27], v[66:67] op_sel_hi:[1,0]
	v_pk_mul_f32 v[24:25], v[24:25], v[66:67] op_sel_hi:[1,0]
	v_pk_mul_f32 v[22:23], v[22:23], v[66:67] op_sel_hi:[1,0]
	v_pk_mul_f32 v[20:21], v[20:21], v[66:67] op_sel_hi:[1,0]
	v_pk_mul_f32 v[18:19], v[18:19], v[66:67] op_sel_hi:[1,0]
	v_mul_f32_e32 v149, v149, v66
	s_branch .LBB0_474

.LBB0_802:
	v_add_u32_e32 v2, s39, v70
	s_sub_i32 s16, s16, s17
	v_subrev_u32_e32 v8, s17, v2
	v_add_u32_e32 v3, s16, v2
	v_max_i32_e32 v11, s19, v8
	v_min_i32_e32 v12, s18, v3
	v_mov_b32_e32 v7, 0
	v_cmp_gt_i32_e32 vcc, v12, v11
	v_mov_b32_e32 v6, v7
	v_mov_b32_e32 v5, v7
	v_mov_b32_e32 v4, v7
	s_and_saveexec_b64 s[16:17], vcc
	s_cbranch_execz .LBB0_806
	s_and_b32 s18, s21, 0xfffff000
	s_ashr_i32 s19, s18, 31
	v_ashrrev_i32_e32 v9, 31, v8
	v_mov_b32_e32 v3, s19
	v_cmp_gt_i64_e32 vcc, s[18:19], v[8:9]
	s_and_b32 s39, s36, 3
	s_nop 0
	v_cndmask_b32_e32 v5, v9, v3, vcc
	v_mov_b32_e32 v3, s18
	v_cndmask_b32_e32 v4, v8, v3, vcc
	v_lshlrev_b64 v[4:5], 11, v[4:5]
	v_lshlrev_b32_e32 v3, 1, v10
	s_lshl_b32 s18, s39, 9
	v_or3_b32 v4, s18, v3, v4
	v_lshl_add_u64 v[8:9], s[10:11], 0, v[4:5]
	v_mov_b32_e32 v4, 0
	v_mov_b32_e32 v5, v4
	v_mov_b32_e32 v6, v4
	v_mov_b32_e32 v7, v4
	v_sub_u32_e32 v3, v12, v11
	s_nop 0
	v_readfirstlane_b32 s18, v3
	global_load_dwordx2 v[20:21], v[8:9], off
	s_cmp_lt_u32 s18, 2
	s_cbranch_scc1 .Lg4fix_w
	v_lshl_add_u64 v[8:9], v[8:9], 0, s[12:13]
	global_load_dwordx2 v[22:23], v[8:9], off
	s_cmp_lt_u32 s18, 3
	s_cbranch_scc1 .Lg4fix_w
	v_lshl_add_u64 v[8:9], v[8:9], 0, s[12:13]
	global_load_dwordx2 v[24:25], v[8:9], off
	s_cmp_lt_u32 s18, 4
	s_cbranch_scc1 .Lg4fix_w
	v_lshl_add_u64 v[8:9], v[8:9], 0, s[12:13]
	global_load_dwordx2 v[26:27], v[8:9], off
	s_cmp_lt_u32 s18, 5
	s_cbranch_scc1 .Lg4fix_w
	v_lshl_add_u64 v[8:9], v[8:9], 0, s[12:13]
	global_load_dwordx2 v[28:29], v[8:9], off
	s_cmp_lt_u32 s18, 6
	s_cbranch_scc1 .Lg4fix_w
	v_lshl_add_u64 v[8:9], v[8:9], 0, s[12:13]
	global_load_dwordx2 v[30:31], v[8:9], off
	s_cmp_lt_u32 s18, 7
	s_cbranch_scc1 .Lg4fix_w
	v_lshl_add_u64 v[8:9], v[8:9], 0, s[12:13]
	global_load_dwordx2 v[32:33], v[8:9], off
	s_cmp_lt_u32 s18, 8
	s_cbranch_scc1 .Lg4fix_w
	v_lshl_add_u64 v[8:9], v[8:9], 0, s[12:13]
	global_load_dwordx2 v[34:35], v[8:9], off
	s_cmp_lt_u32 s18, 9
	s_cbranch_scc1 .Lg4fix_w
	v_lshl_add_u64 v[8:9], v[8:9], 0, s[12:13]
	global_load_dwordx2 v[36:37], v[8:9], off
	s_cmp_lt_u32 s18, 10
	s_cbranch_scc1 .Lg4fix_w
	v_lshl_add_u64 v[8:9], v[8:9], 0, s[12:13]
	global_load_dwordx2 v[38:39], v[8:9], off
	s_cmp_lt_u32 s18, 11
	s_cbranch_scc1 .Lg4fix_w
	v_lshl_add_u64 v[8:9], v[8:9], 0, s[12:13]
	global_load_dwordx2 v[40:41], v[8:9], off
	s_cmp_lt_u32 s18, 12
	s_cbranch_scc1 .Lg4fix_w
	v_lshl_add_u64 v[8:9], v[8:9], 0, s[12:13]
	global_load_dwordx2 v[42:43], v[8:9], off
	s_cmp_lt_u32 s18, 13
	s_cbranch_scc1 .Lg4fix_w
	v_lshl_add_u64 v[8:9], v[8:9], 0, s[12:13]
	global_load_dwordx2 v[44:45], v[8:9], off
	s_cmp_lt_u32 s18, 14
	s_cbranch_scc1 .Lg4fix_w
	v_lshl_add_u64 v[8:9], v[8:9], 0, s[12:13]
	global_load_dwordx2 v[46:47], v[8:9], off
	s_cmp_lt_u32 s18, 15
	s_cbranch_scc1 .Lg4fix_w
	v_lshl_add_u64 v[8:9], v[8:9], 0, s[12:13]
	global_load_dwordx2 v[48:49], v[8:9], off
	s_cmp_lt_u32 s18, 16
	s_cbranch_scc1 .Lg4fix_w
	v_lshl_add_u64 v[8:9], v[8:9], 0, s[12:13]
	global_load_dwordx2 v[50:51], v[8:9], off
.Lg4fix_w:
	s_waitcnt vmcnt(0)
	v_lshlrev_b32_e32 v17, 16, v20
	v_and_b32_e32 v16, 0xffff0000, v20
	v_lshlrev_b32_e32 v19, 16, v21
	v_and_b32_e32 v18, 0xffff0000, v21
	v_pk_add_f32 v[6:7], v[6:7], v[16:17]
	v_pk_add_f32 v[4:5], v[4:5], v[18:19]
	s_cmp_lt_u32 s18, 2
	s_cbranch_scc1 .Lg4fix_d
	v_lshlrev_b32_e32 v17, 16, v22
	v_and_b32_e32 v16, 0xffff0000, v22
	v_lshlrev_b32_e32 v19, 16, v23
	v_and_b32_e32 v18, 0xffff0000, v23
	v_pk_add_f32 v[6:7], v[6:7], v[16:17]
	v_pk_add_f32 v[4:5], v[4:5], v[18:19]
	s_cmp_lt_u32 s18, 3
	s_cbranch_scc1 .Lg4fix_d
	v_lshlrev_b32_e32 v17, 16, v24
	v_and_b32_e32 v16, 0xffff0000, v24
	v_lshlrev_b32_e32 v19, 16, v25
	v_and_b32_e32 v18, 0xffff0000, v25
	v_pk_add_f32 v[6:7], v[6:7], v[16:17]
	v_pk_add_f32 v[4:5], v[4:5], v[18:19]
	s_cmp_lt_u32 s18, 4
	s_cbranch_scc1 .Lg4fix_d
	v_lshlrev_b32_e32 v17, 16, v26
	v_and_b32_e32 v16, 0xffff0000, v26
	v_lshlrev_b32_e32 v19, 16, v27
	v_and_b32_e32 v18, 0xffff0000, v27
	v_pk_add_f32 v[6:7], v[6:7], v[16:17]
	v_pk_add_f32 v[4:5], v[4:5], v[18:19]
	s_cmp_lt_u32 s18, 5
	s_cbranch_scc1 .Lg4fix_d
	v_lshlrev_b32_e32 v17, 16, v28
	v_and_b32_e32 v16, 0xffff0000, v28
	v_lshlrev_b32_e32 v19, 16, v29
	v_and_b32_e32 v18, 0xffff0000, v29
	v_pk_add_f32 v[6:7], v[6:7], v[16:17]
	v_pk_add_f32 v[4:5], v[4:5], v[18:19]
	s_cmp_lt_u32 s18, 6
	s_cbranch_scc1 .Lg4fix_d
	v_lshlrev_b32_e32 v17, 16, v30
	v_and_b32_e32 v16, 0xffff0000, v30
	v_lshlrev_b32_e32 v19, 16, v31
	v_and_b32_e32 v18, 0xffff0000, v31
	v_pk_add_f32 v[6:7], v[6:7], v[16:17]
	v_pk_add_f32 v[4:5], v[4:5], v[18:19]
	s_cmp_lt_u32 s18, 7
	s_cbranch_scc1 .Lg4fix_d
	v_lshlrev_b32_e32 v17, 16, v32
	v_and_b32_e32 v16, 0xffff0000, v32
	v_lshlrev_b32_e32 v19, 16, v33
	v_and_b32_e32 v18, 0xffff0000, v33
	v_pk_add_f32 v[6:7], v[6:7], v[16:17]
	v_pk_add_f32 v[4:5], v[4:5], v[18:19]
	s_cmp_lt_u32 s18, 8
	s_cbranch_scc1 .Lg4fix_d
	v_lshlrev_b32_e32 v17, 16, v34
	v_and_b32_e32 v16, 0xffff0000, v34
	v_lshlrev_b32_e32 v19, 16, v35
	v_and_b32_e32 v18, 0xffff0000, v35
	v_pk_add_f32 v[6:7], v[6:7], v[16:17]
	v_pk_add_f32 v[4:5], v[4:5], v[18:19]
	s_cmp_lt_u32 s18, 9
	s_cbranch_scc1 .Lg4fix_d
	v_lshlrev_b32_e32 v17, 16, v36
	v_and_b32_e32 v16, 0xffff0000, v36
	v_lshlrev_b32_e32 v19, 16, v37
	v_and_b32_e32 v18, 0xffff0000, v37
	v_pk_add_f32 v[6:7], v[6:7], v[16:17]
	v_pk_add_f32 v[4:5], v[4:5], v[18:19]
	s_cmp_lt_u32 s18, 10
	s_cbranch_scc1 .Lg4fix_d
	v_lshlrev_b32_e32 v17, 16, v38
	v_and_b32_e32 v16, 0xffff0000, v38
	v_lshlrev_b32_e32 v19, 16, v39
	v_and_b32_e32 v18, 0xffff0000, v39
	v_pk_add_f32 v[6:7], v[6:7], v[16:17]
	v_pk_add_f32 v[4:5], v[4:5], v[18:19]
	s_cmp_lt_u32 s18, 11
	s_cbranch_scc1 .Lg4fix_d
	v_lshlrev_b32_e32 v17, 16, v40
	v_and_b32_e32 v16, 0xffff0000, v40
	v_lshlrev_b32_e32 v19, 16, v41
	v_and_b32_e32 v18, 0xffff0000, v41
	v_pk_add_f32 v[6:7], v[6:7], v[16:17]
	v_pk_add_f32 v[4:5], v[4:5], v[18:19]
	s_cmp_lt_u32 s18, 12
	s_cbranch_scc1 .Lg4fix_d
	v_lshlrev_b32_e32 v17, 16, v42
	v_and_b32_e32 v16, 0xffff0000, v42
	v_lshlrev_b32_e32 v19, 16, v43
	v_and_b32_e32 v18, 0xffff0000, v43
	v_pk_add_f32 v[6:7], v[6:7], v[16:17]
	v_pk_add_f32 v[4:5], v[4:5], v[18:19]
	s_cmp_lt_u32 s18, 13
	s_cbranch_scc1 .Lg4fix_d
	v_lshlrev_b32_e32 v17, 16, v44
	v_and_b32_e32 v16, 0xffff0000, v44
	v_lshlrev_b32_e32 v19, 16, v45
	v_and_b32_e32 v18, 0xffff0000, v45
	v_pk_add_f32 v[6:7], v[6:7], v[16:17]
	v_pk_add_f32 v[4:5], v[4:5], v[18:19]
	s_cmp_lt_u32 s18, 14
	s_cbranch_scc1 .Lg4fix_d
	v_lshlrev_b32_e32 v17, 16, v46
	v_and_b32_e32 v16, 0xffff0000, v46
	v_lshlrev_b32_e32 v19, 16, v47
	v_and_b32_e32 v18, 0xffff0000, v47
	v_pk_add_f32 v[6:7], v[6:7], v[16:17]
	v_pk_add_f32 v[4:5], v[4:5], v[18:19]
	s_cmp_lt_u32 s18, 15
	s_cbranch_scc1 .Lg4fix_d
	v_lshlrev_b32_e32 v17, 16, v48
	v_and_b32_e32 v16, 0xffff0000, v48
	v_lshlrev_b32_e32 v19, 16, v49
	v_and_b32_e32 v18, 0xffff0000, v49
	v_pk_add_f32 v[6:7], v[6:7], v[16:17]
	v_pk_add_f32 v[4:5], v[4:5], v[18:19]
	s_cmp_lt_u32 s18, 16
	s_cbranch_scc1 .Lg4fix_d
	v_lshlrev_b32_e32 v17, 16, v50
	v_and_b32_e32 v16, 0xffff0000, v50
	v_lshlrev_b32_e32 v19, 16, v51
	v_and_b32_e32 v18, 0xffff0000, v51
	v_pk_add_f32 v[6:7], v[6:7], v[16:17]
	v_pk_add_f32 v[4:5], v[4:5], v[18:19]
.Lg4fix_d:
.LBB0_806:
	s_or_b64 exec, exec, s[16:17]
	v_ashrrev_i32_e32 v3, 31, v2
	v_or_b32_e32 v13, s38, v10
	v_lshlrev_b64 v[2:3], 11, v[2:3]
	v_lshl_add_u64 v[8:9], s[10:11], 0, v[2:3]
	v_lshlrev_b32_e32 v66, 1, v13
	v_lshl_add_u64 v[8:9], v[8:9], 0, v[66:67]
	global_load_dwordx2 v[8:9], v[8:9], off
	v_sub_u32_e32 v11, v12, v11
	v_cvt_f32_i32_e32 v11, v11
	v_lshl_add_u64 v[2:3], s[8:9], 0, v[2:3]
	v_lshl_add_u64 v[2:3], v[2:3], 0, v[66:67]
	v_rcp_iflag_f32_e32 v12, v11
	s_nop 0
	v_pk_mul_f32 v[6:7], v[12:13], v[6:7] op_sel_hi:[0,1]
	v_pk_mul_f32 v[4:5], v[12:13], v[4:5] op_sel_hi:[0,1]
	s_waitcnt vmcnt(0)
	v_lshlrev_b32_e32 v12, 16, v8
	v_and_b32_e32 v13, 0xffff0000, v8
	v_lshlrev_b32_e32 v8, 16, v9
	v_and_b32_e32 v9, 0xffff0000, v9
	v_pk_add_f32 v[6:7], v[6:7], v[12:13] op_sel:[1,0] op_sel_hi:[0,1] neg_lo:[0,1] neg_hi:[0,1]
	v_pk_add_f32 v[4:5], v[4:5], v[8:9] op_sel:[1,0] op_sel_hi:[0,1] neg_lo:[0,1] neg_hi:[0,1]
	v_cvt_pk_bf16_f32 v6, v6, v7
	v_cvt_pk_bf16_f32 v7, v4, v5
	global_store_dwordx2 v[2:3], v[6:7], off
